# FIN phase: slab reduction as 16-deep rolling load pipeline (was 1 dependent round trip per load); rows dealt one per workgroup across all XCDs
# speedup vs baseline: 1.0367x; 1.0367x over previous
.LBB0_1050:
	s_or_b64 exec, exec, s[0:1]
	v_mov_b32_e32 v1, v0
	v_readlane_b32 s0, v253, 12
	v_readlane_b32 s2, v253, 51
	v_readlane_b32 s1, v253, 10
	s_waitcnt lgkmcnt(0)
	s_barrier
	s_mul_i32 s2, s2, s1
	s_add_i32 s0, s0, s2
	s_mov_b64 s[10:11], s[84:85]
	s_cmpk_gt_i32 s0, 0xff
	s_cbranch_scc1 .LBB0_1062
	s_lshl_b32 s8, s1, 3
	s_add_u32 s1, s10, 0x4979c000
	s_addc_u32 s9, s11, 0
	s_add_u32 s2, s10, 0x18400
	s_addc_u32 s3, s11, 0
	s_add_u32 s16, s10, 0x10f80000
	v_readlane_b32 s12, v254, 26
	s_addc_u32 s17, s11, 0
	v_readlane_b32 s13, v254, 27
	v_readlane_b32 s36, v253, 35
	v_and_b32_e32 v1, 63, v1
	s_and_b64 s[12:13], s[12:13], exec
	v_readlane_b32 s38, v253, 37
	v_readlane_b32 s39, v253, 38
	s_cselect_b32 s13, s9, s39
	s_cselect_b32 s12, s1, s38
	v_lshlrev_b32_e32 v6, 4, v1
	v_mov_b32_e32 v7, v4
	v_lshl_add_u64 v[158:159], s[12:13], 0, v[6:7]
	v_readlane_b32 s12, v254, 9
	v_readlane_b32 s13, v254, 10
	v_readlane_b32 s14, v254, 12
	s_cselect_b32 s18, s14, s9
	v_lshl_add_u64 v[160:161], s[12:13], 0, v[6:7]
	s_mov_b64 s[12:13], 0x1000
	v_lshl_add_u64 v[162:163], v[160:161], 0, s[12:13]
	s_mov_b64 s[12:13], 0x1400
	v_lshl_add_u64 v[164:165], v[160:161], 0, s[12:13]
	s_mov_b64 s[12:13], 0x1800
	v_lshl_add_u64 v[166:167], v[160:161], 0, s[12:13]
	s_mov_b64 s[12:13], 0x1c00
	v_lshl_add_u64 v[168:169], v[160:161], 0, s[12:13]
	s_mov_b64 s[12:13], 0x2000
	v_lshl_add_u64 v[170:171], v[160:161], 0, s[12:13]
	s_mov_b64 s[12:13], 0x2400
	v_lshl_add_u64 v[172:173], v[160:161], 0, s[12:13]
	s_mov_b64 s[12:13], 0x2800
	v_lshl_add_u64 v[174:175], v[160:161], 0, s[12:13]
	s_mov_b64 s[12:13], 0x2c00
	v_lshl_add_u64 v[176:177], v[160:161], 0, s[12:13]
	s_mov_b64 s[12:13], 0x3000
	v_lshl_add_u64 v[178:179], v[160:161], 0, s[12:13]
	s_mov_b64 s[12:13], 0x3400
	v_readlane_b32 s9, v254, 11
	v_lshl_add_u64 v[180:181], v[160:161], 0, s[12:13]
	s_mov_b64 s[12:13], 0x3800
	s_cselect_b32 s19, s9, s1
	v_lshl_add_u64 v[182:183], v[160:161], 0, s[12:13]
	s_mov_b64 s[12:13], 0x3c00
	s_ashr_i32 s1, s0, 31
	v_lshl_add_u64 v[184:185], v[160:161], 0, s[12:13]
	s_lshl_b64 s[12:13], s[0:1], 14
	s_add_u32 s10, s10, s12
	v_lshlrev_b32_e32 v2, 2, v1
	s_addc_u32 s11, s11, s13
	s_ashr_i32 s9, s8, 31
	v_cmp_eq_u32_e64 s[6:7], 0, v1
	v_or_b32_e32 v134, 0x400, v2
	v_or_b32_e32 v136, 0x500, v2
	v_or_b32_e32 v138, 0x600, v2
	v_or_b32_e32 v140, 0x700, v2
	v_or_b32_e32 v142, 0x800, v2
	v_or_b32_e32 v144, 0x900, v2
	v_or_b32_e32 v146, 0xa00, v2
	v_or_b32_e32 v148, 0xb00, v2
	v_or_b32_e32 v150, 0xc00, v2
	v_or_b32_e32 v152, 0xd00, v2
	v_or_b32_e32 v154, 0xe00, v2
	v_or_b32_e32 v156, 0xf00, v2
	v_lshl_add_u64 v[186:187], s[10:11], 0, v[6:7]
	s_lshl_b64 s[10:11], s[8:9], 14
	v_readlane_b32 s37, v253, 36
	v_readlane_b32 s40, v253, 39
	v_readlane_b32 s41, v253, 40
	v_readlane_b32 s42, v253, 41
	v_readlane_b32 s43, v253, 42
	v_readlane_b32 s44, v253, 43
	v_readlane_b32 s45, v253, 44
	v_readlane_b32 s46, v253, 45
	v_readlane_b32 s47, v253, 46
	v_readlane_b32 s48, v253, 47
	v_readlane_b32 s49, v253, 48
	v_readlane_b32 s50, v253, 49
	v_readlane_b32 s51, v253, 50
	s_branch .LBB0_1053

.LBB0_1053:
	s_ashr_i32 s1, s0, 31
	s_lshl_b64 s[12:13], s[0:1], 14
	v_lshl_add_u64 v[50:51], v[158:159], 0, s[12:13]
	v_add_co_u32_e32 v30, vcc, 0x1000, v50
	global_load_dwordx4 v[66:69], v[50:51], off
	global_load_dwordx4 v[6:9], v[50:51], off offset:1024
	global_load_dwordx4 v[10:13], v[50:51], off offset:2048
	global_load_dwordx4 v[14:17], v[50:51], off offset:3072
	v_addc_co_u32_e32 v31, vcc, 0, v51, vcc
	v_add_co_u32_e32 v46, vcc, 0x2000, v50
	global_load_dwordx4 v[18:21], v[30:31], off
	global_load_dwordx4 v[22:25], v[30:31], off offset:1024
	global_load_dwordx4 v[26:29], v[30:31], off offset:2048
	s_nop 0
	global_load_dwordx4 v[30:33], v[30:31], off offset:3072
	v_addc_co_u32_e32 v47, vcc, 0, v51, vcc
	v_add_co_u32_e32 v62, vcc, 0x3000, v50
	global_load_dwordx4 v[34:37], v[46:47], off
	global_load_dwordx4 v[38:41], v[46:47], off offset:1024
	global_load_dwordx4 v[42:45], v[46:47], off offset:2048
	s_nop 0
	global_load_dwordx4 v[46:49], v[46:47], off offset:3072
	v_addc_co_u32_e32 v63, vcc, 0, v51, vcc
	global_load_dwordx4 v[50:53], v[62:63], off
	global_load_dwordx4 v[54:57], v[62:63], off offset:1024
	global_load_dwordx4 v[58:61], v[62:63], off offset:2048
	s_nop 0
	global_load_dwordx4 v[62:65], v[62:63], off offset:3072
	v_lshlrev_b32_e32 v188, 2, v2
	s_add_u32 s14, s84, s12
	s_addc_u32 s15, s85, s13
	v_add_u32_e32 v189, 0x2000, v188
	s_add_u32 s14, s14, 0x49c1d000
	s_addc_u32 s15, s15, 0
	v_add_u32_e32 v190, 0x4000, v188
	s_mov_b32 s9, 15
	global_load_dwordx4 v[70:73], v188, s[14:15]
	global_load_dwordx4 v[74:77], v188, s[14:15] offset:1024
	global_load_dwordx4 v[78:81], v188, s[14:15] offset:2048
	global_load_dwordx4 v[82:85], v188, s[14:15] offset:3072
	global_load_dwordx4 v[86:89], v189, s[14:15] offset:-4096
	global_load_dwordx4 v[90:93], v189, s[14:15] offset:-3072
	global_load_dwordx4 v[94:97], v189, s[14:15] offset:-2048
	global_load_dwordx4 v[98:101], v189, s[14:15] offset:-1024
	global_load_dwordx4 v[102:105], v189, s[14:15]
	global_load_dwordx4 v[106:109], v189, s[14:15] offset:1024
	global_load_dwordx4 v[110:113], v189, s[14:15] offset:2048
	global_load_dwordx4 v[114:117], v189, s[14:15] offset:3072
	global_load_dwordx4 v[118:121], v190, s[14:15] offset:-4096
	global_load_dwordx4 v[122:125], v190, s[14:15] offset:-3072
	global_load_dwordx4 v[126:129], v190, s[14:15] offset:-2048
	global_load_dwordx4 v[130:133], v190, s[14:15] offset:-1024
.Lfin_slab_loop:
	s_add_u32 s14, s14, 0x400000
	s_addc_u32 s15, s15, 0
	s_waitcnt vmcnt(15)
	v_pk_add_f32 v[66:67], v[66:67], v[70:71]
	v_pk_add_f32 v[68:69], v[68:69], v[72:73]
	global_load_dwordx4 v[70:73], v188, s[14:15]
	s_waitcnt vmcnt(15)
	v_pk_add_f32 v[6:7], v[6:7], v[74:75]
	v_pk_add_f32 v[8:9], v[8:9], v[76:77]
	global_load_dwordx4 v[74:77], v188, s[14:15] offset:1024
	s_waitcnt vmcnt(15)
	v_pk_add_f32 v[10:11], v[10:11], v[78:79]
	v_pk_add_f32 v[12:13], v[12:13], v[80:81]
	global_load_dwordx4 v[78:81], v188, s[14:15] offset:2048
	s_waitcnt vmcnt(15)
	v_pk_add_f32 v[14:15], v[14:15], v[82:83]
	v_pk_add_f32 v[16:17], v[16:17], v[84:85]
	global_load_dwordx4 v[82:85], v188, s[14:15] offset:3072
	s_waitcnt vmcnt(15)
	v_pk_add_f32 v[18:19], v[18:19], v[86:87]
	v_pk_add_f32 v[20:21], v[20:21], v[88:89]
	global_load_dwordx4 v[86:89], v189, s[14:15] offset:-4096
	s_waitcnt vmcnt(15)
	v_pk_add_f32 v[22:23], v[22:23], v[90:91]
	v_pk_add_f32 v[24:25], v[24:25], v[92:93]
	global_load_dwordx4 v[90:93], v189, s[14:15] offset:-3072
	s_waitcnt vmcnt(15)
	v_pk_add_f32 v[26:27], v[26:27], v[94:95]
	v_pk_add_f32 v[28:29], v[28:29], v[96:97]
	global_load_dwordx4 v[94:97], v189, s[14:15] offset:-2048
	s_waitcnt vmcnt(15)
	v_pk_add_f32 v[30:31], v[30:31], v[98:99]
	v_pk_add_f32 v[32:33], v[32:33], v[100:101]
	global_load_dwordx4 v[98:101], v189, s[14:15] offset:-1024
	s_waitcnt vmcnt(15)
	v_pk_add_f32 v[34:35], v[34:35], v[102:103]
	v_pk_add_f32 v[36:37], v[36:37], v[104:105]
	global_load_dwordx4 v[102:105], v189, s[14:15]
	s_waitcnt vmcnt(15)
	v_pk_add_f32 v[38:39], v[38:39], v[106:107]
	v_pk_add_f32 v[40:41], v[40:41], v[108:109]
	global_load_dwordx4 v[106:109], v189, s[14:15] offset:1024
	s_waitcnt vmcnt(15)
	v_pk_add_f32 v[42:43], v[42:43], v[110:111]
	v_pk_add_f32 v[44:45], v[44:45], v[112:113]
	global_load_dwordx4 v[110:113], v189, s[14:15] offset:2048
	s_waitcnt vmcnt(15)
	v_pk_add_f32 v[46:47], v[46:47], v[114:115]
	v_pk_add_f32 v[48:49], v[48:49], v[116:117]
	global_load_dwordx4 v[114:117], v189, s[14:15] offset:3072
	s_waitcnt vmcnt(15)
	v_pk_add_f32 v[50:51], v[50:51], v[118:119]
	v_pk_add_f32 v[52:53], v[52:53], v[120:121]
	global_load_dwordx4 v[118:121], v190, s[14:15] offset:-4096
	s_waitcnt vmcnt(15)
	v_pk_add_f32 v[54:55], v[54:55], v[122:123]
	v_pk_add_f32 v[56:57], v[56:57], v[124:125]
	global_load_dwordx4 v[122:125], v190, s[14:15] offset:-3072
	s_waitcnt vmcnt(15)
	v_pk_add_f32 v[58:59], v[58:59], v[126:127]
	v_pk_add_f32 v[60:61], v[60:61], v[128:129]
	global_load_dwordx4 v[126:129], v190, s[14:15] offset:-2048
	s_waitcnt vmcnt(15)
	v_pk_add_f32 v[62:63], v[62:63], v[130:131]
	v_pk_add_f32 v[64:65], v[64:65], v[132:133]
	global_load_dwordx4 v[130:133], v190, s[14:15] offset:-1024
	s_sub_i32 s9, s9, 1
	s_cmp_lg_u32 s9, 0
	s_cbranch_scc1 .Lfin_slab_loop
	s_waitcnt vmcnt(15)
	v_pk_add_f32 v[66:67], v[66:67], v[70:71]
	v_pk_add_f32 v[68:69], v[68:69], v[72:73]
	s_waitcnt vmcnt(14)
	v_pk_add_f32 v[6:7], v[6:7], v[74:75]
	v_pk_add_f32 v[8:9], v[8:9], v[76:77]
	s_waitcnt vmcnt(13)
	v_pk_add_f32 v[10:11], v[10:11], v[78:79]
	v_pk_add_f32 v[12:13], v[12:13], v[80:81]
	s_waitcnt vmcnt(12)
	v_pk_add_f32 v[14:15], v[14:15], v[82:83]
	v_pk_add_f32 v[16:17], v[16:17], v[84:85]
	s_waitcnt vmcnt(11)
	v_pk_add_f32 v[18:19], v[18:19], v[86:87]
	v_pk_add_f32 v[20:21], v[20:21], v[88:89]
	s_waitcnt vmcnt(10)
	v_pk_add_f32 v[22:23], v[22:23], v[90:91]
	v_pk_add_f32 v[24:25], v[24:25], v[92:93]
	s_waitcnt vmcnt(9)
	v_pk_add_f32 v[26:27], v[26:27], v[94:95]
	v_pk_add_f32 v[28:29], v[28:29], v[96:97]
	s_waitcnt vmcnt(8)
	v_pk_add_f32 v[30:31], v[30:31], v[98:99]
	v_pk_add_f32 v[32:33], v[32:33], v[100:101]
	s_waitcnt vmcnt(7)
	v_pk_add_f32 v[34:35], v[34:35], v[102:103]
	v_pk_add_f32 v[36:37], v[36:37], v[104:105]
	s_waitcnt vmcnt(6)
	v_pk_add_f32 v[38:39], v[38:39], v[106:107]
	v_pk_add_f32 v[40:41], v[40:41], v[108:109]
	s_waitcnt vmcnt(5)
	v_pk_add_f32 v[42:43], v[42:43], v[110:111]
	v_pk_add_f32 v[44:45], v[44:45], v[112:113]
	s_waitcnt vmcnt(4)
	v_pk_add_f32 v[46:47], v[46:47], v[114:115]
	v_pk_add_f32 v[48:49], v[48:49], v[116:117]
	s_waitcnt vmcnt(3)
	v_pk_add_f32 v[50:51], v[50:51], v[118:119]
	v_pk_add_f32 v[52:53], v[52:53], v[120:121]
	s_waitcnt vmcnt(2)
	v_pk_add_f32 v[54:55], v[54:55], v[122:123]
	v_pk_add_f32 v[56:57], v[56:57], v[124:125]
	s_waitcnt vmcnt(1)
	v_pk_add_f32 v[58:59], v[58:59], v[126:127]
	v_pk_add_f32 v[60:61], v[60:61], v[128:129]
	s_waitcnt vmcnt(0)
	v_pk_add_f32 v[62:63], v[62:63], v[130:131]
	v_pk_add_f32 v[64:65], v[64:65], v[132:133]
	global_load_dwordx4 v[130:133], v[160:161], off
	global_load_dwordx4 v[126:129], v[160:161], off offset:1024
	global_load_dwordx4 v[122:125], v[160:161], off offset:2048
	global_load_dwordx4 v[118:121], v[160:161], off offset:3072
	global_load_dwordx4 v[114:117], v[162:163], off
	global_load_dwordx4 v[110:113], v[164:165], off
	global_load_dwordx4 v[106:109], v[166:167], off
	global_load_dwordx4 v[102:105], v[168:169], off
	global_load_dwordx4 v[98:101], v[170:171], off
	global_load_dwordx4 v[94:97], v[172:173], off
	global_load_dwordx4 v[90:93], v[174:175], off
	global_load_dwordx4 v[86:89], v[176:177], off
	global_load_dwordx4 v[82:85], v[178:179], off
	global_load_dwordx4 v[78:81], v[180:181], off
	global_load_dwordx4 v[74:77], v[182:183], off
	global_load_dwordx4 v[70:73], v[184:185], off
	s_add_u32 s12, s19, s12
	s_addc_u32 s13, s18, s13
	v_lshlrev_b32_e32 v190, 2, v2
	v_mov_b32_e32 v191, v4
	v_lshl_add_u64 v[188:189], s[12:13], 0, v[190:191]
	s_mov_b64 s[14:15], -1
	s_andn2_b64 vcc, exec, s[60:61]
	v_lshlrev_b32_e32 v1, 2, v134
	v_lshlrev_b32_e32 v3, 2, v136
	v_lshlrev_b32_e32 v5, 2, v138
	v_lshlrev_b32_e32 v135, 2, v140
	v_lshlrev_b32_e32 v137, 2, v142
	v_lshlrev_b32_e32 v139, 2, v144
	v_lshlrev_b32_e32 v141, 2, v146
	v_lshlrev_b32_e32 v143, 2, v148
	v_lshlrev_b32_e32 v145, 2, v150
	v_lshlrev_b32_e32 v147, 2, v152
	v_lshlrev_b32_e32 v149, 2, v154
	v_lshlrev_b32_e32 v151, 2, v156
	global_store_dwordx4 v190, v[66:69], s[12:13]
	s_cbranch_vccz .LBB0_1057
	s_andn2_b64 vcc, exec, s[14:15]
	s_cbranch_vccnz .LBB0_1052
	s_branch .LBB0_1060
